# GLA item remap: the four dv slices of one (batch, head) chain placed on one XCD (shared L2 for q/k/decay loads), on top of the pipelined mem conversion
# speedup vs baseline: 1.0074x; 1.0074x over previous
; __device__ void gla_item(const Params& p, int item, LAS unsigned char* lds) {
;     ...
;     const int b = item >> 4, hh = (item >> 2) & 3, sl = item & 3;
;     constexpr int QS0 = 0, KS = 34816, VS0 = 52224, ST0 = 70656, AS = 105472;
;     const unsigned lbase = (unsigned)(size_t)lds;
;     unsigned char* ws = p.ws;
;     const bf16_t* h = (const bf16_t*)(ws + OFF_H);
;     bf16_t* og = (bf16_t*)(ws + OFF_OG);
;     const int t = tid >> 3, cgp = tid & 7;
;     const bf16_t* hq = h + (size_t)(b * SEQ) * HC + hh * 128 + cgp * 16;
;     const bf16_t* hv = h + (size_t)(b * SEQ) * HC + 1024 + hh * 256 + sl * 64 + cgp * 8;
;     const bf16_t* pdec = (const bf16_t*)(ws + OFF_EB) + (size_t)(b * SEQ) * 512 + hh * 128 + 16 * w + 4 * g;
.LBB0_18:
	s_add_u32 s4, s92, 0x12d00000
	s_addc_u32 s5, s93, 0
	s_add_u32 s66, s92, 0x6b00000
	s_addc_u32 s67, s93, 0
	s_add_u32 s68, s92, 0x8100000
	s_addc_u32 s69, s93, 0
	s_lshl_b32 s35, s34, 9
	s_lshl_b32 s70, s60, 9
	s_add_u32 s54, s92, 0x4000000
	s_addc_u32 s55, s93, 0
	s_add_u32 s22, s92, 0x11100000
	s_addc_u32 s23, s93, 0
	s_add_u32 s64, s92, 0x19100000
	s_addc_u32 s65, s93, 0
	s_lshl_b32 s11, s34, 3
	v_writelane_b32 v251, s4, 10
	s_cmp_lg_u64 s[92:93], 0
	s_load_dwordx16 s[36:51], s[0:1], 0x40
	v_writelane_b32 v251, s5, 11
	s_cselect_b64 s[4:5], -1, 0
	v_writelane_b32 v251, s4, 12
	s_load_dwordx16 s[72:87], s[0:1], 0x0
	v_mbcnt_lo_u32_b32 v0, -1, 0
	v_writelane_b32 v251, s5, 13
	s_lshl_b32 s4, s60, 3
	s_cmpk_lt_i32 s34, 0x560
	v_writelane_b32 v251, s4, 14
	s_cselect_b64 s[4:5], -1, 0
	v_writelane_b32 v251, s4, 15
	s_lshl_b32 s14, s34, 6
	s_ashr_i32 s6, s34, 5
	v_writelane_b32 v251, s5, 16
	s_and_b32 s4, s14, 0x7c0
	v_writelane_b32 v251, s4, 17
	s_lshl_b32 s4, s6, 7
	v_writelane_b32 v251, s4, 18
	s_lshl_b32 s4, s6, 8
	s_add_u32 s26, s92, 0xd100000
	s_addc_u32 s27, s93, 0
	v_writelane_b32 v251, s4, 19
	s_add_u32 s4, s92, 0xb800000
	s_addc_u32 s5, s93, 0
	v_writelane_b32 v251, s4, 20
	v_mbcnt_hi_u32_b32 v215, -1, v0
	v_and_b32_e32 v0, 64, v215
	v_writelane_b32 v251, s5, 21
	s_add_u32 s4, s92, 0xa000000
	s_addc_u32 s5, s93, 0
	v_writelane_b32 v251, s4, 22
	v_mov_b32_e32 v3, 0
	v_mov_b32_e32 v213, 0x3727c5ac
	v_writelane_b32 v251, s5, 23
	s_add_u32 s4, s92, 0x9800000
	s_addc_u32 s5, s93, 0
	v_writelane_b32 v251, s4, 24
	v_mov_b32_e32 v214, 1
	v_add_u32_e32 v216, 64, v0
	v_writelane_b32 v251, s5, 25
	s_add_u32 s4, s92, 0x6000000
	s_addc_u32 s5, s93, 0
	s_add_u32 s24, s92, 0x1b100000
	v_writelane_b32 v251, s4, 26
	s_addc_u32 s25, s93, 0
	v_xor_b32_e32 v217, 32, v215
	v_writelane_b32 v251, s5, 27
	s_add_u32 s4, s92, 0xcc00000
	s_addc_u32 s5, s93, 0
	v_writelane_b32 v251, s4, 28
	s_cmp_gt_i32 s34, 63
	v_xor_b32_e32 v218, 16, v215
	v_writelane_b32 v251, s5, 29
	s_cselect_b64 s[4:5], -1, 0
	v_writelane_b32 v251, s4, 30
	s_cmpk_lt_u32 s34, 0x80
	v_xor_b32_e32 v250, 1, v215
	v_writelane_b32 v251, s5, 31
	s_cselect_b64 s[4:5], -1, 0
	v_writelane_b32 v251, s4, 32
	v_mov_b32_e32 v219, 0x6600
	v_mov_b32_e32 v224, 0x8800
	v_writelane_b32 v251, s5, 33
	s_sub_i32 s4, s34, 64
	s_add_u32 s30, s92, 0xc400000
	s_addc_u32 s31, s93, 0
	v_writelane_b32 v251, s4, 34
	s_add_u32 s4, s92, 0xa800000
	s_addc_u32 s5, s93, 0
	v_writelane_b32 v251, s4, 35
	v_mov_b32_e32 v225, 0xaa00
	v_mov_b32_e32 v226, 0xcc00
	v_writelane_b32 v251, s5, 36
	s_add_u32 s4, s92, 0xc000000
	s_addc_u32 s5, s93, 0
	v_writelane_b32 v251, s4, 37
	v_mov_b32_e32 v227, 0xee00
	v_mov_b32_e32 v228, 0xf149f2ca
	v_writelane_b32 v251, s5, 38
	s_and_b32 s4, s34, 7
	s_lshl_b32 s4, s4, 1
	s_lshr_b32 s5, s34, 3
	s_lshr_b32 s7, s5, 2
	s_add_i32 s4, s4, s7
	s_lshl_b32 s4, s4, 2
	s_and_b32 s5, s5, 3
	s_or_b32 s32, s4, s5
	s_lshl_b32 s5, s32, 8
	s_and_b32 s16, s5, 0xfffff000
	s_bfe_u32 s4, s32, 0x20002
	s_ashr_i32 s17, s16, 31
	s_mul_i32 s7, s16, 0x3000
	s_mul_hi_i32 s5, s16, 0x3000
	s_add_u32 s7, s26, s7
	s_addc_u32 s5, s27, s5
	s_lshl_b32 s8, s4, 8
	s_add_u32 s18, s7, s8
	s_addc_u32 s19, s5, 0
	s_lshl_b32 s9, s4, 9
	s_add_u32 s4, s7, s9
	s_addc_u32 s5, s5, 0
	s_lshl_b32 s10, s34, 7
	s_lshl_b32 s7, s32, 7
	s_and_b32 s7, s7, 0x180
	v_writelane_b32 v251, s18, 39
	s_add_u32 s4, s4, s7
	s_addc_u32 s5, s5, 0
	v_writelane_b32 v251, s19, 40
	v_writelane_b32 v251, s4, 41
	s_add_u32 s18, s92, 0x1d100000
	s_addc_u32 s19, s93, 0
	v_writelane_b32 v251, s5, 42
	s_mov_b32 s4, s16
	v_writelane_b32 v251, s4, 43
	s_mov_b32 s98, 0xbfb8aa3b
	s_movk_i32 s99, 0x110
	v_writelane_b32 v251, s5, 44
	s_lshl_b64 s[4:5], s[16:17], 10
	s_add_u32 s4, s18, s4
	v_writelane_b32 v251, s18, 45
	s_addc_u32 s5, s19, s5
	s_add_u32 s4, s4, s8
	v_writelane_b32 v251, s19, 46
	v_writelane_b32 v251, s4, 47
	s_addc_u32 s4, s5, 0
	v_writelane_b32 v251, s4, 48
	s_add_u32 s4, s64, s9
	s_addc_u32 s5, s65, 0
	s_add_u32 s4, s4, s7
	v_writelane_b32 v251, s4, 49
	s_addc_u32 s4, s5, 0
	v_writelane_b32 v251, s4, 50
	s_add_u32 s4, s92, 0x8000000
	s_addc_u32 s5, s93, 0
	v_writelane_b32 v251, s4, 51
	s_mov_b32 s19, 0
	s_mov_b32 s52, 0x3d8293ee
	v_writelane_b32 v251, s5, 52
	s_add_u32 s4, s92, 0xce01000
	s_addc_u32 s5, s93, 0
	v_writelane_b32 v251, s4, 53
	s_cmp_eq_u32 s34, 0
	s_movk_i32 s33, 0x7f
	v_writelane_b32 v251, s5, 54
	s_cselect_b64 s[4:5], -1, 0
	v_writelane_b32 v251, s4, 55
	s_movk_i32 s29, 0x81
	s_movk_i32 s28, 0xff7e
	v_writelane_b32 v251, s5, 56
	s_add_u32 s4, s92, 0xce00000
	s_addc_u32 s5, s93, 0
	v_writelane_b32 v251, s4, 57
	s_cmpk_lt_i32 s34, 0x100
	s_movk_i32 s53, 0x7e
	v_writelane_b32 v251, s5, 58
	s_cselect_b64 s[4:5], -1, 0
	v_writelane_b32 v251, s4, 59
	s_mov_b64 s[20:21], 0x80
	s_nop 0
	v_writelane_b32 v251, s5, 60
	s_lshl_b32 s4, s34, 1
	s_add_i32 s5, s4, 16
	s_and_b32 s5, s5, 48
	v_writelane_b32 v251, s5, 61
	s_and_b32 s5, s4, 48
	s_add_i32 s4, s4, 48
	s_and_b32 s4, s4, 48
	v_writelane_b32 v251, s4, 62
	s_xor_b32 s4, s5, 32
	s_cmpk_lt_i32 s34, 0x500
	v_writelane_b32 v251, s5, 63
	v_writelane_b32 v252, s4, 0
	s_cselect_b64 s[4:5], -1, 0
	v_writelane_b32 v252, s4, 1
	s_nop 1
	v_writelane_b32 v252, s5, 2
	s_add_i32 s4, s34, 0x200
	s_cmpk_lt_i32 s34, 0x300
	s_cselect_b32 s7, s34, s4
	s_cmpk_gt_i32 s7, 0x2ff
	s_cselect_b64 s[4:5], -1, 0
	v_writelane_b32 v252, s4, 3
	s_cmpk_gt_u32 s7, 0x3ff
	s_nop 0
	v_writelane_b32 v252, s5, 4
	s_cselect_b64 s[4:5], -1, 0
	s_lshl_b32 s8, s7, 3
	v_writelane_b32 v252, s4, 5
	s_cmpk_lt_u32 s7, 0x500
	s_nop 0
	v_writelane_b32 v252, s5, 6
	s_cselect_b64 s[4:5], -1, 0
	s_and_b32 s9, s8, 0x1f00
; __device__ __forceinline__ unsigned xb_ld(unsigned* p)              { return __hip_atomic_load(p, __ATOMIC_RELAXED, __HIP_MEMORY_SCOPE_AGENT); }
; __device__ __forceinline__ unsigned xb_add(unsigned* p, unsigned v) { return __hip_atomic_fetch_add(p, v, __ATOMIC_RELAXED, __HIP_MEMORY_SCOPE_AGENT); }
; __device__ __forceinline__ unsigned xb_xcc_id() { return (unsigned)__builtin_amdgcn_s_getreg((3 << 11) | 20) & 0xFu; }
; __device__ __forceinline__ XcdBarrier xcd_barrier_post(unsigned* bar, volatile LAS unsigned* st) {
;     XcdBarrier b; b.bar = bar; b.x = xb_xcc_id(); b.st = st;
;     if (threadIdx.x == 0) (void)xb_add(&bar[XB_XCNT(b.x)], 1u);
;     return b;
; }
; __device__ __forceinline__ void xcd_barrier_complete(unsigned* bar, unsigned x, unsigned& nloc, unsigned& nx) {
;     const unsigned G = gridDim.x * gridDim.y * gridDim.z;
;     unsigned sum, cnt, mine, sp = 0u;
;     for (;;) {
;         sum = 0u; cnt = 0u; mine = 0u;
; #pragma unroll
;         for (unsigned j = 0; j < 16; ++j) { const unsigned c = xb_ld(&bar[XB_XCNT(j)]); sum += c; cnt += (c > 0u) ? 1u : 0u; mine = (j == x) ? c : mine; }
;         if (sum == G) break;
;         __builtin_amdgcn_s_sleep(1);
;         if ((++sp & 255u) == 0u) { if (xb_ld(&bar[XB_TMO])) break; if (sp > XB_SPIN_CAP) { atomicAdd(&bar[XB_TMO], 1u); break; } }
;     }
;     nloc = mine > 0u ? mine : 1u; nx = cnt > 0u ? cnt : 1u;
; }
	s_add_i32 s13, s9, 0xffffe800
	v_writelane_b32 v252, s13, 7
	s_addk_i32 s9, 0xe880
	v_writelane_b32 v252, s9, 8
	s_and_b32 s9, s8, 0x3f00
	s_and_b32 s15, s8, 0xffffff00
	s_cmpk_gt_i32 s15, 0xbff
	s_cselect_b32 s8, 16, 0
	v_writelane_b32 v252, s11, 9
	s_and_b32 s11, s11, 56
	s_add_i32 s11, s11, s6
	s_lshl_b32 s6, s11, 3
	s_lshl_b32 s13, s34, 2
	s_and_b32 s6, s6, 0xffffff80
	s_and_b32 s13, s13, 0x60
	s_or_b32 s13, s6, s13
	s_lshl_b32 s6, s7, 6
	v_writelane_b32 v252, s15, 10
	s_and_b32 s6, s6, 0x7c0
	v_writelane_b32 v252, s6, 11
	s_lshl_b32 s6, s11, 4
	s_and_b32 s6, s6, 0xffffff00
	s_or_b32 s15, s8, s15
	s_ashr_i32 s7, s6, 31
	s_lshl_b32 s8, s11, 1
	s_lshl_b64 s[6:7], s[6:7], 13
	s_or_b32 s11, s15, 0x80
	s_add_u32 s6, s30, s6
	s_addc_u32 s7, s31, s7
	s_and_b32 s10, s10, 0xc00
	v_writelane_b32 v252, s15, 12
	s_add_u32 s6, s6, s10
	v_writelane_b32 v252, s11, 13
	s_addc_u32 s7, s7, 0
	v_writelane_b32 v252, s6, 14
	s_nop 1
	v_writelane_b32 v252, s7, 15
	s_and_b32 s6, s8, 30
	s_or_b32 s10, s13, s6
	s_cmpk_gt_i32 s34, 0xbf
	s_cselect_b64 s[6:7], -1, 0
	v_writelane_b32 v252, s6, 16
	s_cmpk_lt_u32 s34, 0x370
	s_nop 0
	v_writelane_b32 v252, s7, 17
	s_cselect_b64 s[6:7], -1, 0
	v_writelane_b32 v252, s6, 18
	s_nop 1
	v_writelane_b32 v252, s7, 19
	s_add_i32 s6, s34, 0xff40
	s_and_b32 s7, s6, 0xffff
	s_mul_i32 s7, s7, 0xbe83
	s_lshr_b32 s7, s7, 22
	s_mul_i32 s8, s7, 0x56
	s_sub_i32 s6, s6, s8
	s_lshl_b32 s6, s6, 6
	s_and_b32 s6, s6, 0xffc0
	v_writelane_b32 v252, s6, 20
	s_lshl_b32 s6, s7, 8
	v_writelane_b32 v252, s6, 21
	s_bitset1_b32 s6, 7
	v_writelane_b32 v252, s6, 22
	s_add_u32 s6, s92, 0x1f400200
	s_addc_u32 s7, s93, 0
	v_writelane_b32 v252, s6, 23
	s_nop 1
	v_writelane_b32 v252, s7, 24
	s_add_u32 s6, s92, 0x1f400400
	s_addc_u32 s7, s93, 0
	v_writelane_b32 v252, s6, 25
	s_nop 1
	v_writelane_b32 v252, s7, 26
	s_add_u32 s6, s92, 0x1f400500
	s_addc_u32 s7, s93, 0
	v_writelane_b32 v252, s6, 27
	s_nop 1
	v_writelane_b32 v252, s7, 28
	s_add_u32 s6, s92, 0x1f400600
	s_addc_u32 s7, s93, 0
	v_writelane_b32 v252, s6, 29
	s_nop 1
	v_writelane_b32 v252, s7, 30
	s_add_u32 s6, s92, 0x1f400700
	s_addc_u32 s7, s93, 0
	v_writelane_b32 v252, s6, 31
	s_nop 1
	v_writelane_b32 v252, s7, 32
	s_add_u32 s6, s92, 0x1f400800
	s_addc_u32 s7, s93, 0
	v_writelane_b32 v252, s6, 33
	s_nop 1
	v_writelane_b32 v252, s7, 34
	s_add_u32 s6, s92, 0x1f400900
	s_addc_u32 s7, s93, 0
	v_writelane_b32 v252, s6, 35
	s_nop 1
	v_writelane_b32 v252, s7, 36
	s_add_u32 s6, s92, 0x1f400a00
	s_addc_u32 s7, s93, 0
	v_writelane_b32 v252, s6, 37
	s_nop 1
	v_writelane_b32 v252, s7, 38
	s_add_u32 s6, s92, 0x1f400b00
	s_addc_u32 s7, s93, 0
	v_writelane_b32 v252, s6, 39
	s_nop 1
	v_writelane_b32 v252, s7, 40
	s_add_u32 s6, s92, 0x1f400c00
	s_addc_u32 s7, s93, 0
	v_writelane_b32 v252, s6, 41
	s_nop 1
	v_writelane_b32 v252, s7, 42
	s_add_u32 s6, s92, 0x1f400d00
	s_addc_u32 s7, s93, 0
	v_writelane_b32 v252, s6, 43
	s_nop 1
	v_writelane_b32 v252, s7, 44
	s_add_u32 s6, s92, 0x1f400e00
	s_addc_u32 s7, s93, 0
	v_writelane_b32 v252, s6, 45
	s_nop 1
	v_writelane_b32 v252, s7, 46
	s_add_u32 s6, s92, 0x1f400f00
	s_addc_u32 s7, s93, 0
	v_writelane_b32 v252, s6, 47
	s_nop 1
	v_writelane_b32 v252, s7, 48
	s_add_u32 s6, s92, 0x1f401000
	s_addc_u32 s7, s93, 0
	v_writelane_b32 v252, s6, 49
	s_nop 1
	v_writelane_b32 v252, s7, 50
	s_add_u32 s6, s92, 0x1f401100
	s_addc_u32 s7, s93, 0
	v_writelane_b32 v252, s6, 51
	s_nop 1
	v_writelane_b32 v252, s7, 52
	s_add_u32 s6, s92, 0x1f401200
	s_addc_u32 s7, s93, 0
	v_writelane_b32 v252, s6, 53
	s_nop 1
	v_writelane_b32 v252, s7, 54
	s_add_u32 s6, s92, 0x1f401300
	s_addc_u32 s7, s93, 0
	v_writelane_b32 v252, s6, 55
	s_cmp_eq_u32 s12, 15
	s_nop 0
	v_writelane_b32 v252, s7, 56
	s_cselect_b64 s[6:7], -1, 0
	v_writelane_b32 v252, s6, 57
	s_cmp_eq_u32 s12, 14
	s_nop 0
	v_writelane_b32 v252, s7, 58
	s_cselect_b64 s[6:7], -1, 0
	v_writelane_b32 v252, s6, 59
	s_cmp_eq_u32 s12, 13
	s_nop 0
	v_writelane_b32 v252, s7, 60
	s_cselect_b64 s[6:7], -1, 0
	v_writelane_b32 v252, s6, 61
	s_cmp_eq_u32 s12, 12
	s_nop 0
	v_writelane_b32 v252, s7, 62
	s_cselect_b64 s[6:7], -1, 0
	v_writelane_b32 v252, s6, 63
	s_cmp_eq_u32 s12, 11
	s_nop 0
	v_writelane_b32 v253, s7, 0
	s_cselect_b64 s[6:7], -1, 0
	v_writelane_b32 v253, s6, 1
	s_cmp_eq_u32 s12, 10
	s_nop 0
	v_writelane_b32 v253, s7, 2
	s_cselect_b64 s[6:7], -1, 0
	v_writelane_b32 v253, s6, 3
	s_cmp_eq_u32 s12, 9
	s_nop 0
	v_writelane_b32 v253, s7, 4
	s_cselect_b64 s[6:7], -1, 0
	v_writelane_b32 v253, s6, 5
	s_cmp_eq_u32 s12, 8
	s_nop 0
	v_writelane_b32 v253, s7, 6
	s_cselect_b64 s[6:7], -1, 0
	v_writelane_b32 v253, s6, 7
	s_cmp_eq_u32 s12, 7
	s_nop 0
	v_writelane_b32 v253, s7, 8
	s_cselect_b64 s[6:7], -1, 0
	v_writelane_b32 v253, s6, 9
	s_cmp_eq_u32 s12, 6
	s_nop 0
	v_writelane_b32 v253, s7, 10
	s_cselect_b64 s[6:7], -1, 0
	v_writelane_b32 v253, s6, 11
	s_cmp_eq_u32 s12, 5
	s_nop 0
	v_writelane_b32 v253, s7, 12
	s_cselect_b64 s[6:7], -1, 0
	v_writelane_b32 v253, s6, 13
	s_cmp_eq_u32 s12, 4
	s_nop 0
	v_writelane_b32 v253, s7, 14
	s_cselect_b64 s[6:7], -1, 0
	v_writelane_b32 v253, s6, 15
	s_cmp_eq_u32 s12, 3
	s_nop 0
	v_writelane_b32 v253, s7, 16
	s_cselect_b64 s[6:7], -1, 0
	v_writelane_b32 v253, s6, 17
	s_cmp_eq_u32 s12, 2
	s_nop 0
	v_writelane_b32 v253, s7, 18
	s_cselect_b64 s[6:7], -1, 0
	v_writelane_b32 v253, s6, 19
	s_cmp_eq_u32 s12, 1
	s_nop 0
	v_writelane_b32 v253, s7, 20
	s_cselect_b64 s[6:7], -1, 0
	v_writelane_b32 v253, s6, 21
	s_cmp_eq_u32 s12, 0
	s_nop 0
	v_writelane_b32 v253, s7, 22
	s_cselect_b64 s[6:7], -1, 0
	v_writelane_b32 v253, s6, 23
	s_nop 1
	v_writelane_b32 v253, s7, 24
	s_lshl_b32 s6, s12, 8
	s_add_u32 s2, s2, s6
	s_addc_u32 s3, s3, 0
	s_add_u32 s6, s2, 0x1400
	s_addc_u32 s7, s3, 0
	v_writelane_b32 v253, s6, 25
	s_add_u32 s2, s2, 0x2400
	s_addc_u32 s3, s3, 0
	v_writelane_b32 v253, s7, 26
	v_writelane_b32 v253, s2, 27
	s_nop 1
	v_writelane_b32 v253, s3, 28
	s_add_u32 s2, s92, 0x1f403400
	s_addc_u32 s3, s93, 0
	v_writelane_b32 v253, s2, 29
	s_nop 1
	v_writelane_b32 v253, s3, 30
	s_add_u32 s2, s92, 0x1f403500
	s_addc_u32 s3, s93, 0
	v_writelane_b32 v253, s2, 31
	s_nop 1
	v_writelane_b32 v253, s3, 32
	s_and_b64 s[2:3], s[4:5], exec
	s_waitcnt lgkmcnt(0)
; #define LAS __attribute__((address_space(3)))
; __global__ void __launch_bounds__(512, 2) fwd_megakernel(Params p) {
;     extern __shared__ __attribute__((aligned(16))) unsigned char smem[];
;     LAS unsigned char* lds = (LAS unsigned char*)smem;
;     cg::grid_group grid = cg::this_grid();
;     unsigned char* ws = p.ws;
;     const int G = (int)gridDim.x, bid = (int)blockIdx.x;
;     if (threadIdx.x < 2) *(LAS unsigned*)(lds + LDS_SLOT + 16 + 4 * threadIdx.x) = 0u;
;     __syncthreads();
;     const XcdBarrier xb = xcd_barrier_post((unsigned*)(ws + OFF_BAR), (volatile LAS unsigned*)(lds + LDS_SLOT + 16));
;     if (p.ph_lo < 0) grid.sync();
;     for (int ph = p.ph_lo; ph < p.ph_hi; ++ph) {
	s_cselect_b32 s3, s41, s43
	v_writelane_b32 v253, s36, 33
	s_cselect_b32 s2, s40, s42
	s_nop 0
	v_writelane_b32 v253, s37, 34
	v_writelane_b32 v253, s38, 35
	v_writelane_b32 v253, s39, 36
	v_writelane_b32 v253, s40, 37
	v_writelane_b32 v253, s41, 38
	v_writelane_b32 v253, s42, 39
	v_writelane_b32 v253, s43, 40
	v_writelane_b32 v253, s44, 41
	v_writelane_b32 v253, s45, 42
	v_writelane_b32 v253, s46, 43
	v_writelane_b32 v253, s47, 44
	v_writelane_b32 v253, s48, 45
	v_writelane_b32 v253, s49, 46
	v_writelane_b32 v253, s50, 47
	v_writelane_b32 v253, s51, 48
	v_writelane_b32 v253, s2, 49
	s_mov_b32 s44, 0x6dc9c883
	s_mov_b32 s45, 0x3fc45f30
	v_writelane_b32 v253, s3, 50
	s_mov_b32 s3, 0xa000000
	s_cselect_b32 s18, s3, 0xa800000
	s_movk_i32 s3, 0x800
	s_movk_i32 s2, 0xe000
	s_cselect_b32 s6, s3, 0x1000
	s_cselect_b32 s2, s2, 0xffffd800
	v_writelane_b32 v253, s6, 51
	s_add_i32 s2, s9, s2
	s_movk_i32 s48, 0x3000
	v_writelane_b32 v253, s7, 52
	v_writelane_b32 v253, s2, 53
	s_and_b64 s[2:3], s[4:5], exec
	s_movk_i32 s2, 0xe080
	s_cselect_b32 s2, s2, 0xffffd880
	s_add_i32 s2, s9, s2
	v_writelane_b32 v253, s2, 54
	s_load_dword s2, s[0:1], 0xc8
	s_mov_b32 s49, 0xf149f2ca
	s_waitcnt lgkmcnt(0)
	s_mul_i32 s2, s61, s2
	s_mul_i32 s2, s2, s60
	v_writelane_b32 v253, s2, 55
	s_add_i32 s2, s34, s60
	s_lshl_b32 s2, s2, 6
	v_writelane_b32 v253, s2, 56
	s_lshl_b32 s2, s60, 6
	v_writelane_b32 v253, s2, 57
	v_writelane_b32 v253, s10, 58
	s_lshl_b32 s2, s10, 4
	v_writelane_b32 v253, s2, 59
	s_add_u32 s2, s92, 0xd100080
	s_addc_u32 s3, s93, 0
	v_writelane_b32 v253, s2, 60
	s_add_i32 s38, 0, 0x22000
	s_mov_b32 s61, 0x3fb8aa3b
	v_writelane_b32 v253, s3, 61
	v_writelane_b32 v253, s14, 62
	s_add_i32 s2, s14, 0x12800
	v_writelane_b32 v253, s2, 63
	s_add_i32 s2, s34, 0x4e0
	v_writelane_b32 v254, s2, 0
	s_add_i32 s2, 0, 0x12000
	v_writelane_b32 v254, s2, 1
	s_add_i32 s2, 0, 0x9000
	v_writelane_b32 v254, s2, 2
	s_add_i32 s2, 0, 0x1a800
	v_writelane_b32 v254, s2, 3
	s_add_i32 s2, 0, 0xd800
	v_writelane_b32 v254, s2, 4
	s_add_i32 s2, 0, 0x16400
	v_writelane_b32 v254, s2, 5
	s_add_i32 s2, 0, 0xfc00
	v_writelane_b32 v254, s2, 6
	s_add_i32 s2, 0, 0x22010
	v_writelane_b32 v254, s2, 7
	s_add_i32 s2, 0, 0x22014
	v_writelane_b32 v254, s2, 8
	v_writelane_b32 v254, s18, 9
	s_add_i32 s14, 0, 0x11080
	s_nop 0
	v_writelane_b32 v254, s19, 10
	v_writelane_b32 v254, s22, 11
	s_nop 1
	v_writelane_b32 v254, s23, 12
	v_writelane_b32 v254, s64, 13
	s_nop 1
	v_writelane_b32 v254, s65, 14
	v_writelane_b32 v254, s26, 15
	s_nop 1
	v_writelane_b32 v254, s27, 16
	v_writelane_b32 v254, s24, 17
	s_nop 1
	v_writelane_b32 v254, s25, 18
	v_writelane_b32 v254, s38, 19
	v_writelane_b32 v254, s34, 20
	v_writelane_b32 v254, s60, 21
	s_nop 1
	v_writelane_b32 v254, s61, 22
	v_writelane_b32 v254, s62, 23
	s_nop 1
	v_writelane_b32 v254, s63, 24
	v_writelane_b32 v254, s66, 25
	s_nop 1
	v_writelane_b32 v254, s67, 26
	v_writelane_b32 v254, s68, 27
	s_nop 1
	v_writelane_b32 v254, s69, 28
	v_writelane_b32 v254, s35, 29
	v_writelane_b32 v254, s70, 30
	v_writelane_b32 v254, s54, 31
	s_nop 1
	v_writelane_b32 v254, s55, 32
	s_branch .LBB0_22
